# plus partial-merge gate loads hoisted above the K-loop
# baseline (speedup 1.0000x reference)
;     DEVINL bf16_t* Pbr() const { return (bf16_t*)(ws + OFF_PBR); }
;     DEVINL bf16_t* Y() const { return (bf16_t*)(ws + OFF_Y); }
; #define TID (opq_v((int)threadIdx.x))
; template <int NI>
; DEVINL void gemm_kloop(const bf16_t* __restrict__ A, int lda, const bf16_t* __restrict__ Bt, int ldb, int K, int m0, int n0,
;                        unsigned char* lds, f32x16 (&acc)[NI][2]) {
;     const int tid = TID, lane = tid & 63, w = tid >> 6, wm = w & 3, wn = w >> 2, r = lane & 31, h = lane >> 5;
;     const int lrow = tid >> 3, cg = (tid & 7) ^ ((tid >> 4) & 7);
;     const bf16_t* ga = A + (size_t)(m0 + lrow) * lda + cg * 8;
;     const bf16_t* gb = Bt + (size_t)(n0 + lrow) * ldb + cg * 8;
;     unsigned char* da = lds + tid * 16;
;     unsigned char* db = lds + A_ST + tid * 16;
;     ...
;     const int nt = K >> 6;
;     asm volatile("s_waitcnt lgkmcnt(0)" ::: "memory");
;     __builtin_amdgcn_s_barrier();
;     GEMM_ISSUE(0, 0);
;     if (nt > 1) GEMM_ISSUE(1, 1);
;     const int sw = (r >> 1) & 7;
;     int o4[4];
; #pragma unroll
;     for (int ks = 0; ks < 4; ++ks) o4[ks] = ((ks * 2 + h) ^ sw) * 16;
; template <int NI, int MODE>
; DEVINL void merge_tile(const Ctx& c, unsigned char* lds, int m0, int n0) {
;     ...
;     for (int bi = 0; bi < (MODE == 0 ? 3 : 1); ++bi) {
;         const int br = (MODE == 0) ? (bi == 2 ? 3 : bi) : 2;
;         f32x16 acc[NI][2]; zero_acc(acc);
;         gemm_kloop<NI>(c.Y() + (size_t)br * T * 512, 512, c.Pbr() + (size_t)br * DM * 512, 512, 512, m0, n0, lds, acc);
.LBB0_284:
	s_cmp_lg_u32 s6, 2
	v_mov_b32_e32 v6, v160
	s_cselect_b32 s66, s6, 3
	s_lshl_b32 s8, s66, 11
	s_mov_b32 s9, 0
	v_lshl_add_u64 v[254:255], v[146:147], 0, s[8:9]
	v_lshl_add_u64 v[242:243], v[148:149], 0, s[8:9]
	global_load_dwordx2 v[208:209], v[254:255], off
	global_load_dwordx2 v[210:211], v[254:255], off offset:16
	global_load_dwordx2 v[212:213], v[254:255], off offset:32
	global_load_dwordx2 v[214:215], v[254:255], off offset:48
	global_load_dwordx2 v[216:217], v[254:255], off offset:64
	global_load_dwordx2 v[218:219], v[254:255], off offset:80
	global_load_dwordx2 v[228:229], v[254:255], off offset:96
	global_load_dwordx2 v[254:255], v[254:255], off offset:112
	global_load_dwordx2 v[230:231], v[242:243], off
	global_load_dwordx2 v[232:233], v[242:243], off offset:16
	global_load_dwordx2 v[234:235], v[242:243], off offset:32
	global_load_dwordx2 v[236:237], v[242:243], off offset:48
	global_load_dwordx2 v[248:249], v[242:243], off offset:64
	global_load_dwordx2 v[250:251], v[242:243], off offset:80
	global_load_dwordx2 v[252:253], v[242:243], off offset:96
	global_load_dwordx2 v[242:243], v[242:243], off offset:112
	s_mul_i32 s8, s66, 0x1100000
	v_ashrrev_i32_e32 v2, 3, v6
	v_lshrrev_b32_e32 v0, 4, v6
	v_xor_b32_e32 v3, v0, v6
	v_add_u32_e32 v0, s1, v2
	s_mul_hi_u32 s7, s66, 0x1100000
	s_add_u32 s8, s86, s8
	v_ashrrev_i32_e32 v1, 31, v0
	s_addc_u32 s9, s87, s7
	v_lshlrev_b64 v[0:1], 10, v[0:1]
	v_lshlrev_b32_e32 v3, 4, v3
	v_lshl_add_u64 v[0:1], s[8:9], 0, v[0:1]
	v_and_b32_e32 v64, 0x70, v3
	s_lshl_b64 s[10:11], s[66:67], 20
	v_lshl_add_u64 v[150:151], v[0:1], 0, v[64:65]
	v_add_u32_e32 v0, s5, v2
	s_add_u32 s10, s43, s10
	v_ashrrev_i32_e32 v1, 31, v0
	s_addc_u32 s11, s38, s11
	v_lshlrev_b64 v[0:1], 10, v[0:1]
	v_lshl_add_u64 v[2:3], s[10:11], 0, v[0:1]
	v_lshl_add_u32 v0, v6, 4, 0
	v_add_u32_e32 v7, 0x2000, v0
	v_readfirstlane_b32 s18, v0
	s_mov_b32 m0, s18
	v_readfirstlane_b32 s17, v7
	v_add_u32_e32 v7, 0x4000, v0
	s_waitcnt lgkmcnt(0)
	s_barrier
	global_load_lds_dwordx4 v[150:151], off
	v_lshl_add_u64 v[4:5], v[150:151], 0, s[74:75]
	s_mov_b32 m0, s17
	v_readfirstlane_b32 s16, v7
	v_add_u32_e32 v7, 0x6000, v0
	v_add_u32_e32 v1, 0x8000, v0
	global_load_lds_dwordx4 v[4:5], off
	v_lshl_add_u64 v[4:5], v[150:151], 0, s[60:61]
	s_mov_b32 m0, s16
	v_readfirstlane_b32 s15, v7
	global_load_lds_dwordx4 v[4:5], off
	v_lshl_add_u64 v[4:5], v[150:151], 0, s[34:35]
	s_mov_b32 m0, s15
	v_readfirstlane_b32 s14, v1
	v_add_u32_e32 v1, 0xa000, v0
	global_load_lds_dwordx4 v[4:5], off
	v_lshl_add_u64 v[152:153], v[2:3], 0, v[64:65]
	s_mov_b32 m0, s14
	v_readfirstlane_b32 s13, v1
	v_add_u32_e32 v1, 0xc000, v0
	global_load_lds_dwordx4 v[152:153], off
	v_lshl_add_u64 v[2:3], v[152:153], 0, s[74:75]
	s_mov_b32 m0, s13
	v_readfirstlane_b32 s12, v1
	v_add_u32_e32 v1, 0xe000, v0
	global_load_lds_dwordx4 v[2:3], off
	v_lshl_add_u64 v[2:3], v[150:151], 0, s[92:93]
	s_mov_b32 m0, s12
	v_readfirstlane_b32 s11, v1
	v_add_u32_e32 v1, 0x10000, v0
	global_load_lds_dwordx4 v[2:3], off
	v_lshl_add_u64 v[2:3], v[150:151], 0, s[76:77]
	s_mov_b32 m0, s11
	v_readfirstlane_b32 s10, v1
	v_add_u32_e32 v1, 0x12000, v0
	global_load_lds_dwordx4 v[2:3], off
	v_lshl_add_u64 v[2:3], v[150:151], 0, s[48:49]
	s_mov_b32 m0, s10
	v_readfirstlane_b32 s9, v1
	v_add_u32_e32 v1, 0x14000, v0
	global_load_lds_dwordx4 v[2:3], off
	v_lshl_add_u64 v[2:3], v[150:151], 0, s[36:37]
	s_mov_b32 m0, s9
	v_readfirstlane_b32 s8, v1
	v_add_u32_e32 v1, 0x16000, v0
	global_load_lds_dwordx4 v[2:3], off
	v_lshl_add_u64 v[2:3], v[152:153], 0, s[92:93]
	s_mov_b32 m0, s8
	v_readfirstlane_b32 s7, v1
	global_load_lds_dwordx4 v[2:3], off
	v_lshl_add_u64 v[2:3], v[152:153], 0, s[76:77]
	s_mov_b32 m0, s7
	v_lshrrev_b32_e32 v1, 5, v6
	global_load_lds_dwordx4 v[2:3], off
	v_bfe_u32 v2, v6, 5, 1
	v_bfe_u32 v3, v6, 1, 3
	v_bitop3_b32 v4, v2, v3, 6 bitop3:0x36
	v_bitop3_b32 v1, v1, v3, 1 bitop3:0x6c
	v_lshlrev_b32_e32 v172, 4, v4
	v_bitop3_b32 v4, v2, v3, 4 bitop3:0x36
	v_bitop3_b32 v2, v2, v3, 2 bitop3:0x36
	v_lshlrev_b32_e32 v175, 4, v1
	v_lshlrev_b32_e32 v1, 7, v6
	v_lshlrev_b32_e32 v174, 4, v2
	v_and_b32_e32 v2, 0xf80, v1
	v_and_b32_e32 v177, 0x6f80, v1
	v_lshlrev_b32_e32 v1, 5, v6
	v_and_or_b32 v176, v1, s29, v2
	v_add_u32_e32 v1, 0x18000, v0
	v_lshl_add_u64 v[2:3], v[150:151], 0, s[84:85]
	v_readfirstlane_b32 s20, v1
	v_add_u32_e32 v1, 0x1a000, v0
	s_mov_b32 m0, s20
	v_readfirstlane_b32 s19, v1
	v_add_u32_e32 v1, 0x1c000, v0
	s_waitcnt vmcnt(6)
	s_barrier
; #define MFMA32(a, b, c) __builtin_amdgcn_mfma_f32_32x32x16_bf16((a), (b), (c), 0, 0, 0)
; template <int NI>
; DEVINL void gemm_kloop(const bf16_t* __restrict__ A, int lda, const bf16_t* __restrict__ Bt, int ldb, int K, int m0, int n0,
;                        unsigned char* lds, f32x16 (&acc)[NI][2]) {
;     ...
;     const int nt = K >> 6;
;     asm volatile("s_waitcnt lgkmcnt(0)" ::: "memory");
;     __builtin_amdgcn_s_barrier();
;     GEMM_ISSUE(0, 0);
;     if (nt > 1) GEMM_ISSUE(1, 1);
;     const int sw = (r >> 1) & 7;
;     int o4[4];
; #pragma unroll
;     for (int ks = 0; ks < 4; ++ks) o4[ks] = ((ks * 2 + h) ^ sw) * 16;
;     int cur = 0;
;     auto compute = [&](int st_) {
;         const unsigned char* pa = lds + st_ * STAGE + (wm * 64 + r) * 128;
;         const unsigned char* pb = lds + st_ * STAGE + A_ST + (wn * 32 * NI + r) * 128;
;         bf16x8 af[2][2], bfr[2][NI];
; #pragma unroll
;         for (int i = 0; i < 2; ++i) af[0][i] = *(const bf16x8*)(pa + i * 32 * 128 + o4[0]);
; #pragma unroll
;         for (int i = 0; i < NI; ++i) bfr[0][i] = *(const bf16x8*)(pb + i * 32 * 128 + o4[0]);
; #pragma unroll
;         for (int ks = 0; ks < 4; ++ks) {
;             if (ks < 3) {
; #pragma unroll
;                 for (int i = 0; i < 2; ++i) af[(ks + 1) & 1][i] = *(const bf16x8*)(pa + i * 32 * 128 + o4[ks + 1]);
; #pragma unroll
;                 for (int i = 0; i < NI; ++i) bfr[(ks + 1) & 1][i] = *(const bf16x8*)(pb + i * 32 * 128 + o4[ks + 1]);
;             }
; #pragma unroll
;             for (int ni = 0; ni < NI; ++ni)
; #pragma unroll
;                 for (int mi = 0; mi < 2; ++mi) acc[ni][mi] = MFMA32(bfr[ks & 1][ni], af[ks & 1][mi], acc[ni][mi]);
;         }
;     };
;     int t = 0;
;     for (; t + 2 < nt; ++t) {
;         if (NI == 2) asm volatile("s_waitcnt vmcnt(6)" ::: "memory"); else asm volatile("s_waitcnt vmcnt(5)" ::: "memory");
;         __builtin_amdgcn_s_barrier();
;         { const int s2 = (cur >= 1) ? cur - 1 : 2; GEMM_ISSUE(s2, t + 2); }
;         compute(cur);
;         cur = (cur == 2) ? 0 : cur + 1;
;     }
	global_load_lds_dwordx4 v[2:3], off
	v_lshl_add_u64 v[2:3], v[150:151], 0, s[78:79]
	s_mov_b32 m0, s19
	v_readfirstlane_b32 s21, v1
	v_add_u32_e32 v1, 0x1e000, v0
	global_load_lds_dwordx4 v[2:3], off
	v_lshl_add_u64 v[2:3], v[150:151], 0, s[30:31]
	s_mov_b32 m0, s21
	v_readfirstlane_b32 s24, v1
	v_add_u32_e32 v1, 0x20000, v0
	global_load_lds_dwordx4 v[2:3], off
	v_lshl_add_u64 v[2:3], v[150:151], 0, s[50:51]
	s_mov_b32 m0, s24
	v_readfirstlane_b32 s25, v1
	v_add_u32_e32 v0, 0x22000, v0
	global_load_lds_dwordx4 v[2:3], off
	v_lshl_add_u64 v[2:3], v[152:153], 0, s[84:85]
	s_mov_b32 m0, s25
	v_readfirstlane_b32 s26, v0
	global_load_lds_dwordx4 v[2:3], off
	v_lshl_add_u64 v[2:3], v[152:153], 0, s[78:79]
	s_mov_b32 m0, s26
	v_add_u32_e32 v156, 0, v177
	v_add_u32_e32 v159, 0, v176
	global_load_lds_dwordx4 v[2:3], off
	v_add_u32_e32 v64, v156, v175
	v_add_u32_e32 v143, v159, v175
	v_lshlrev_b32_e32 v173, 4, v4
	ds_read_b128 v[4:7], v64
	ds_read_b128 v[0:3], v64 offset:4096
	ds_read_b128 v[8:11], v143 offset:32768
	ds_read_b128 v[12:15], v143 offset:36864
	s_waitcnt lgkmcnt(0)
	v_mfma_f32_32x32x16_bf16 v[48:63], v[8:11], v[4:7], 0
	v_add_u32_e32 v154, v156, v174
	v_add_u32_e32 v157, v159, v174
	ds_read_b128 v[130:133], v154
	ds_read_b128 v[134:137], v154 offset:4096
	ds_read_b128 v[168:171], v157 offset:32768
	ds_read_b128 v[178:181], v157 offset:36864
	v_add_u32_e32 v155, v156, v173
	v_add_u32_e32 v158, v159, v173
	ds_read_b128 v[182:185], v155
	ds_read_b128 v[186:189], v155 offset:4096
	v_mfma_f32_32x32x16_bf16 v[32:47], v[12:15], v[4:7], 0
	ds_read_b128 v[190:193], v158 offset:32768
	ds_read_b128 v[194:197], v158 offset:36864
	v_add_u32_e32 v156, v156, v172
	v_add_u32_e32 v159, v159, v172
	s_mov_b32 m0, s18
	s_add_i32 s27, 0, 0x14000
	v_add_u32_e32 v207, s42, v176
	s_lshl_b32 s66, s66, 11
	v_mfma_f32_32x32x16_bf16 v[16:31], v[8:11], v[0:3], 0
	s_add_i32 s6, s6, 1
	v_mfma_f32_32x32x16_bf16 v[0:15], v[12:15], v[0:3], 0
	s_waitcnt lgkmcnt(0)
	v_mfma_f32_32x32x16_bf16 v[48:63], v[168:171], v[130:133], v[48:63]
	v_mfma_f32_32x32x16_bf16 v[32:47], v[178:181], v[130:133], v[32:47]
	v_mfma_f32_32x32x16_bf16 v[16:31], v[168:171], v[134:137], v[16:31]
	v_mfma_f32_32x32x16_bf16 v[0:15], v[178:181], v[134:137], v[0:15]
	ds_read_b128 v[130:133], v156
	ds_read_b128 v[134:137], v156 offset:4096
	ds_read_b128 v[168:171], v159 offset:32768
	ds_read_b128 v[178:181], v159 offset:36864
	s_waitcnt vmcnt(6)
	s_barrier
	v_mfma_f32_32x32x16_bf16 v[48:63], v[190:193], v[182:185], v[48:63]
	v_mfma_f32_32x32x16_bf16 v[32:47], v[194:197], v[182:185], v[32:47]
	v_mfma_f32_32x32x16_bf16 v[16:31], v[190:193], v[186:189], v[16:31]
	v_mfma_f32_32x32x16_bf16 v[0:15], v[194:197], v[186:189], v[0:15]
	s_waitcnt lgkmcnt(0)
	v_mfma_f32_32x32x16_bf16 v[48:63], v[168:171], v[130:133], v[48:63]
	v_mfma_f32_32x32x16_bf16 v[32:47], v[178:181], v[130:133], v[32:47]
	v_lshl_add_u64 v[130:131], v[150:151], 0, s[88:89]
	global_load_lds_dwordx4 v[130:131], off
	v_lshl_add_u64 v[130:131], v[150:151], 0, s[80:81]
	s_mov_b32 m0, s17
	s_nop 0
	global_load_lds_dwordx4 v[130:131], off
	v_lshl_add_u64 v[130:131], v[150:151], 0, s[96:97]
	s_mov_b32 m0, s16
	v_mfma_f32_32x32x16_bf16 v[16:31], v[168:171], v[134:137], v[16:31]
	global_load_lds_dwordx4 v[130:131], off
	v_lshl_add_u64 v[130:131], v[150:151], 0, s[52:53]
	s_mov_b32 m0, s15
	v_add_u32_e32 v171, s27, v176
	global_load_lds_dwordx4 v[130:131], off
	v_lshl_add_u64 v[130:131], v[152:153], 0, s[88:89]
	s_mov_b32 m0, s14
	v_mfma_f32_32x32x16_bf16 v[0:15], v[178:181], v[134:137], v[0:15]
	global_load_lds_dwordx4 v[130:131], off
	v_lshl_add_u64 v[130:131], v[152:153], 0, s[80:81]
	s_mov_b32 m0, s13
	v_add_u32_e32 v168, v171, v175
	global_load_lds_dwordx4 v[130:131], off
	ds_read_b128 v[134:137], v64 offset:49152
	ds_read_b128 v[130:133], v64 offset:53248
	ds_read_b128 v[178:181], v168
	ds_read_b128 v[182:185], v168 offset:4096
	ds_read_b128 v[186:189], v154 offset:49152
	ds_read_b128 v[190:193], v154 offset:53248
	s_waitcnt lgkmcnt(0)
	v_mfma_f32_32x32x16_bf16 v[48:63], v[178:181], v[134:137], v[48:63]
	v_add_u32_e32 v169, v171, v174
	ds_read_b128 v[194:197], v169
	ds_read_b128 v[198:201], v169 offset:4096
	v_add_u32_e32 v170, v171, v173
	v_add_u32_e32 v171, v171, v172
	s_mov_b32 m0, s12
	s_add_i32 s27, 0, 0x18000
	v_add_u32_e32 v206, s27, v177
	v_mfma_f32_32x32x16_bf16 v[32:47], v[182:185], v[134:137], v[32:47]
	v_add_u32_e32 v177, v206, v175
	v_add_u32_e32 v175, v207, v175
	v_add_u32_e32 v176, v206, v174
	v_add_u32_e32 v174, v207, v174
	s_cmp_lg_u32 s6, 3
	v_mfma_f32_32x32x16_bf16 v[16:31], v[178:181], v[130:133], v[16:31]
	v_mfma_f32_32x32x16_bf16 v[0:15], v[182:185], v[130:133], v[0:15]
	ds_read_b128 v[130:133], v155 offset:49152
	ds_read_b128 v[134:137], v155 offset:53248
	ds_read_b128 v[178:181], v170
	ds_read_b128 v[182:185], v170 offset:4096
	s_waitcnt lgkmcnt(0)
	v_mfma_f32_32x32x16_bf16 v[48:63], v[194:197], v[186:189], v[48:63]
	v_mfma_f32_32x32x16_bf16 v[32:47], v[198:201], v[186:189], v[32:47]
	v_mfma_f32_32x32x16_bf16 v[16:31], v[194:197], v[190:193], v[16:31]
	v_mfma_f32_32x32x16_bf16 v[0:15], v[198:201], v[190:193], v[0:15]
	ds_read_b128 v[186:189], v156 offset:49152
	ds_read_b128 v[190:193], v156 offset:53248
	ds_read_b128 v[194:197], v171
	ds_read_b128 v[198:201], v171 offset:4096
	s_waitcnt vmcnt(6)
	s_barrier
; #define MFMA32(a, b, c) __builtin_amdgcn_mfma_f32_32x32x16_bf16((a), (b), (c), 0, 0, 0)
; template <int NI>
; DEVINL void gemm_kloop(const bf16_t* __restrict__ A, int lda, const bf16_t* __restrict__ Bt, int ldb, int K, int m0, int n0,
;                        unsigned char* lds, f32x16 (&acc)[NI][2]) {
;     ...
;     const int nt = K >> 6;
;     asm volatile("s_waitcnt lgkmcnt(0)" ::: "memory");
;     __builtin_amdgcn_s_barrier();
;     GEMM_ISSUE(0, 0);
;     if (nt > 1) GEMM_ISSUE(1, 1);
;     const int sw = (r >> 1) & 7;
;     int o4[4];
; #pragma unroll
;     for (int ks = 0; ks < 4; ++ks) o4[ks] = ((ks * 2 + h) ^ sw) * 16;
;     int cur = 0;
;     auto compute = [&](int st_) {
;         const unsigned char* pa = lds + st_ * STAGE + (wm * 64 + r) * 128;
;         const unsigned char* pb = lds + st_ * STAGE + A_ST + (wn * 32 * NI + r) * 128;
;         bf16x8 af[2][2], bfr[2][NI];
; #pragma unroll
;         for (int i = 0; i < 2; ++i) af[0][i] = *(const bf16x8*)(pa + i * 32 * 128 + o4[0]);
; #pragma unroll
;         for (int i = 0; i < NI; ++i) bfr[0][i] = *(const bf16x8*)(pb + i * 32 * 128 + o4[0]);
; #pragma unroll
;         for (int ks = 0; ks < 4; ++ks) {
;             if (ks < 3) {
; #pragma unroll
;                 for (int i = 0; i < 2; ++i) af[(ks + 1) & 1][i] = *(const bf16x8*)(pa + i * 32 * 128 + o4[ks + 1]);
; #pragma unroll
;                 for (int i = 0; i < NI; ++i) bfr[(ks + 1) & 1][i] = *(const bf16x8*)(pb + i * 32 * 128 + o4[ks + 1]);
;             }
; #pragma unroll
;             for (int ni = 0; ni < NI; ++ni)
; #pragma unroll
;                 for (int mi = 0; mi < 2; ++mi) acc[ni][mi] = MFMA32(bfr[ks & 1][ni], af[ks & 1][mi], acc[ni][mi]);
;         }
;     };
;     int t = 0;
;     for (; t + 2 < nt; ++t) {
;         if (NI == 2) asm volatile("s_waitcnt vmcnt(6)" ::: "memory"); else asm volatile("s_waitcnt vmcnt(5)" ::: "memory");
;         __builtin_amdgcn_s_barrier();
;         { const int s2 = (cur >= 1) ? cur - 1 : 2; GEMM_ISSUE(s2, t + 2); }
;         compute(cur);
;         cur = (cur == 2) ? 0 : cur + 1;
;     }
	v_mfma_f32_32x32x16_bf16 v[48:63], v[178:181], v[130:133], v[48:63]
	v_mfma_f32_32x32x16_bf16 v[32:47], v[182:185], v[130:133], v[32:47]
	v_lshl_add_u64 v[130:131], v[150:151], 0, s[58:59]
	global_load_lds_dwordx4 v[130:131], off
	v_lshl_add_u64 v[130:131], v[150:151], 0, s[82:83]
	s_mov_b32 m0, s11
	s_nop 0
	global_load_lds_dwordx4 v[130:131], off
	v_lshl_add_u64 v[130:131], v[150:151], 0, s[62:63]
	s_mov_b32 m0, s10
	v_mfma_f32_32x32x16_bf16 v[16:31], v[178:181], v[134:137], v[16:31]
	global_load_lds_dwordx4 v[130:131], off
	v_lshl_add_u64 v[130:131], v[150:151], 0, s[54:55]
	s_mov_b32 m0, s9
	s_nop 0
	global_load_lds_dwordx4 v[130:131], off
	v_mfma_f32_32x32x16_bf16 v[0:15], v[182:185], v[134:137], v[0:15]
	v_lshl_add_u64 v[130:131], v[152:153], 0, s[58:59]
	s_mov_b32 m0, s8
	s_nop 0
	global_load_lds_dwordx4 v[130:131], off
	v_lshl_add_u64 v[130:131], v[152:153], 0, s[82:83]
	s_mov_b32 m0, s7
	s_waitcnt lgkmcnt(0)
	v_mfma_f32_32x32x16_bf16 v[48:63], v[194:197], v[186:189], v[48:63]
	global_load_lds_dwordx4 v[130:131], off
	ds_read_b128 v[134:137], v177
	ds_read_b128 v[130:133], v177 offset:4096
	ds_read_b128 v[178:181], v175
	ds_read_b128 v[182:185], v175 offset:4096
	s_mov_b32 m0, s20
	v_mfma_f32_32x32x16_bf16 v[32:47], v[198:201], v[186:189], v[32:47]
	v_mfma_f32_32x32x16_bf16 v[16:31], v[194:197], v[190:193], v[16:31]
	v_mfma_f32_32x32x16_bf16 v[0:15], v[198:201], v[190:193], v[0:15]
	ds_read_b128 v[186:189], v176
	ds_read_b128 v[190:193], v176 offset:4096
	ds_read_b128 v[194:197], v174
	ds_read_b128 v[198:201], v174 offset:4096
	s_waitcnt lgkmcnt(0)
	v_mfma_f32_32x32x16_bf16 v[48:63], v[178:181], v[134:137], v[48:63]
	v_mfma_f32_32x32x16_bf16 v[32:47], v[182:185], v[134:137], v[32:47]
	v_mfma_f32_32x32x16_bf16 v[16:31], v[178:181], v[130:133], v[16:31]
	v_mfma_f32_32x32x16_bf16 v[0:15], v[182:185], v[130:133], v[0:15]
	v_add_u32_e32 v130, v206, v173
	v_add_u32_e32 v131, v207, v173
	ds_read_b128 v[134:137], v130
	ds_read_b128 v[178:181], v130 offset:4096
	ds_read_b128 v[182:185], v131
	ds_read_b128 v[202:205], v131 offset:4096
	v_add_u32_e32 v132, v206, v172
	v_add_u32_e32 v133, v207, v172
	v_mfma_f32_32x32x16_bf16 v[48:63], v[194:197], v[186:189], v[48:63]
	v_mfma_f32_32x32x16_bf16 v[32:47], v[198:201], v[186:189], v[32:47]
	v_mfma_f32_32x32x16_bf16 v[16:31], v[194:197], v[190:193], v[16:31]
	v_mfma_f32_32x32x16_bf16 v[0:15], v[198:201], v[190:193], v[0:15]
	ds_read_b128 v[186:189], v132
	ds_read_b128 v[190:193], v132 offset:4096
	ds_read_b128 v[194:197], v133
	ds_read_b128 v[198:201], v133 offset:4096
	s_waitcnt vmcnt(6)
	s_barrier
	s_waitcnt lgkmcnt(0)
	v_mfma_f32_32x32x16_bf16 v[48:63], v[182:185], v[134:137], v[48:63]
	v_mfma_f32_32x32x16_bf16 v[32:47], v[202:205], v[134:137], v[32:47]
	v_lshl_add_u64 v[134:135], v[150:151], 0, s[64:65]
	global_load_lds_dwordx4 v[134:135], off
	v_lshl_add_u64 v[134:135], v[150:151], 0, s[68:69]
	s_mov_b32 m0, s19
	s_nop 0
	global_load_lds_dwordx4 v[134:135], off
	v_mfma_f32_32x32x16_bf16 v[16:31], v[182:185], v[178:181], v[16:31]
	v_lshl_add_u64 v[134:135], v[150:151], 0, s[90:91]
	s_mov_b32 m0, s21
	s_nop 0
	global_load_lds_dwordx4 v[134:135], off
	v_lshl_add_u64 v[134:135], v[150:151], 0, s[94:95]
	s_mov_b32 m0, s24
	v_mfma_f32_32x32x16_bf16 v[0:15], v[202:205], v[178:181], v[0:15]
	global_load_lds_dwordx4 v[134:135], off
	v_lshl_add_u64 v[134:135], v[152:153], 0, s[64:65]
	s_mov_b32 m0, s25
	s_nop 0
	global_load_lds_dwordx4 v[134:135], off
	v_mfma_f32_32x32x16_bf16 v[48:63], v[194:197], v[186:189], v[48:63]
	v_lshl_add_u64 v[134:135], v[152:153], 0, s[68:69]
	s_mov_b32 m0, s26
	s_nop 0
	global_load_lds_dwordx4 v[134:135], off
	s_mov_b32 m0, s18
	v_mfma_f32_32x32x16_bf16 v[32:47], v[198:201], v[186:189], v[32:47]
	v_mfma_f32_32x32x16_bf16 v[16:31], v[194:197], v[190:193], v[16:31]
	v_mfma_f32_32x32x16_bf16 v[0:15], v[198:201], v[190:193], v[0:15]
	ds_read_b128 v[134:137], v64
	ds_read_b128 v[178:181], v64 offset:4096
	ds_read_b128 v[182:185], v143 offset:32768
	ds_read_b128 v[186:189], v143 offset:36864
	ds_read_b128 v[190:193], v154
	ds_read_b128 v[194:197], v154 offset:4096
	ds_read_b128 v[198:201], v157 offset:32768
	ds_read_b128 v[202:205], v157 offset:36864
	s_waitcnt lgkmcnt(0)
	v_mfma_f32_32x32x16_bf16 v[48:63], v[182:185], v[134:137], v[48:63]
	v_mfma_f32_32x32x16_bf16 v[32:47], v[186:189], v[134:137], v[32:47]
	v_mfma_f32_32x32x16_bf16 v[16:31], v[182:185], v[178:181], v[16:31]
	v_mfma_f32_32x32x16_bf16 v[0:15], v[186:189], v[178:181], v[0:15]
	ds_read_b128 v[134:137], v155
	ds_read_b128 v[178:181], v155 offset:4096
	ds_read_b128 v[182:185], v158 offset:32768
	ds_read_b128 v[186:189], v158 offset:36864
	v_mfma_f32_32x32x16_bf16 v[48:63], v[198:201], v[190:193], v[48:63]
	v_mfma_f32_32x32x16_bf16 v[32:47], v[202:205], v[190:193], v[32:47]
	v_mfma_f32_32x32x16_bf16 v[16:31], v[198:201], v[194:197], v[16:31]
	v_mfma_f32_32x32x16_bf16 v[0:15], v[202:205], v[194:197], v[0:15]
	ds_read_b128 v[190:193], v156
	ds_read_b128 v[194:197], v156 offset:4096
	ds_read_b128 v[198:201], v159 offset:32768
	ds_read_b128 v[202:205], v159 offset:36864
	s_waitcnt vmcnt(6)
	s_barrier
; #define MFMA32(a, b, c) __builtin_amdgcn_mfma_f32_32x32x16_bf16((a), (b), (c), 0, 0, 0)
; template <int NI>
; DEVINL void gemm_kloop(const bf16_t* __restrict__ A, int lda, const bf16_t* __restrict__ Bt, int ldb, int K, int m0, int n0,
;                        unsigned char* lds, f32x16 (&acc)[NI][2]) {
;     ...
;     const int nt = K >> 6;
;     asm volatile("s_waitcnt lgkmcnt(0)" ::: "memory");
;     __builtin_amdgcn_s_barrier();
;     GEMM_ISSUE(0, 0);
;     if (nt > 1) GEMM_ISSUE(1, 1);
;     const int sw = (r >> 1) & 7;
;     int o4[4];
; #pragma unroll
;     for (int ks = 0; ks < 4; ++ks) o4[ks] = ((ks * 2 + h) ^ sw) * 16;
;     int cur = 0;
;     auto compute = [&](int st_) {
;         const unsigned char* pa = lds + st_ * STAGE + (wm * 64 + r) * 128;
;         const unsigned char* pb = lds + st_ * STAGE + A_ST + (wn * 32 * NI + r) * 128;
;         bf16x8 af[2][2], bfr[2][NI];
; #pragma unroll
;         for (int i = 0; i < 2; ++i) af[0][i] = *(const bf16x8*)(pa + i * 32 * 128 + o4[0]);
; #pragma unroll
;         for (int i = 0; i < NI; ++i) bfr[0][i] = *(const bf16x8*)(pb + i * 32 * 128 + o4[0]);
; #pragma unroll
;         for (int ks = 0; ks < 4; ++ks) {
;             if (ks < 3) {
; #pragma unroll
;                 for (int i = 0; i < 2; ++i) af[(ks + 1) & 1][i] = *(const bf16x8*)(pa + i * 32 * 128 + o4[ks + 1]);
; #pragma unroll
;                 for (int i = 0; i < NI; ++i) bfr[(ks + 1) & 1][i] = *(const bf16x8*)(pb + i * 32 * 128 + o4[ks + 1]);
;             }
; #pragma unroll
;             for (int ni = 0; ni < NI; ++ni)
; #pragma unroll
;                 for (int mi = 0; mi < 2; ++mi) acc[ni][mi] = MFMA32(bfr[ks & 1][ni], af[ks & 1][mi], acc[ni][mi]);
;         }
;     };
;     int t = 0;
;     for (; t + 2 < nt; ++t) {
;         if (NI == 2) asm volatile("s_waitcnt vmcnt(6)" ::: "memory"); else asm volatile("s_waitcnt vmcnt(5)" ::: "memory");
;         __builtin_amdgcn_s_barrier();
;         { const int s2 = (cur >= 1) ? cur - 1 : 2; GEMM_ISSUE(s2, t + 2); }
;         compute(cur);
;         cur = (cur == 2) ? 0 : cur + 1;
;     }
	s_waitcnt lgkmcnt(0)
	v_mfma_f32_32x32x16_bf16 v[48:63], v[182:185], v[134:137], v[48:63]
	v_mfma_f32_32x32x16_bf16 v[32:47], v[186:189], v[134:137], v[32:47]
	v_lshl_add_u64 v[134:135], v[150:151], 0, s[2:3]
	global_load_lds_dwordx4 v[134:135], off
	v_lshl_add_u64 v[134:135], v[150:151], 0, s[70:71]
	s_mov_b32 m0, s17
	s_nop 0
	global_load_lds_dwordx4 v[134:135], off
	v_mfma_f32_32x32x16_bf16 v[16:31], v[182:185], v[178:181], v[16:31]
	v_lshl_add_u64 v[134:135], v[150:151], 0, s[72:73]
	s_mov_b32 m0, s16
	s_nop 0
	global_load_lds_dwordx4 v[134:135], off
	v_lshl_add_u64 v[134:135], v[150:151], 0, vcc
	s_mov_b32 m0, s15
	v_mfma_f32_32x32x16_bf16 v[0:15], v[186:189], v[178:181], v[0:15]
	global_load_lds_dwordx4 v[134:135], off
	v_lshl_add_u64 v[134:135], v[152:153], 0, s[2:3]
	s_mov_b32 m0, s14
	s_nop 0
	global_load_lds_dwordx4 v[134:135], off
	v_mfma_f32_32x32x16_bf16 v[48:63], v[198:201], v[190:193], v[48:63]
	v_lshl_add_u64 v[134:135], v[152:153], 0, s[70:71]
	s_mov_b32 m0, s13
	s_nop 0
	global_load_lds_dwordx4 v[134:135], off
	s_mov_b32 m0, s12
	v_mfma_f32_32x32x16_bf16 v[32:47], v[202:205], v[190:193], v[32:47]
	v_mfma_f32_32x32x16_bf16 v[16:31], v[198:201], v[194:197], v[16:31]
	v_mfma_f32_32x32x16_bf16 v[0:15], v[202:205], v[194:197], v[0:15]
	ds_read_b128 v[134:137], v64 offset:49152
	ds_read_b128 v[178:181], v64 offset:53248
	ds_read_b128 v[182:185], v168
	ds_read_b128 v[186:189], v168 offset:4096
	ds_read_b128 v[190:193], v154 offset:49152
	ds_read_b128 v[194:197], v154 offset:53248
	ds_read_b128 v[198:201], v169
	ds_read_b128 v[202:205], v169 offset:4096
	s_waitcnt lgkmcnt(0)
	v_mfma_f32_32x32x16_bf16 v[48:63], v[182:185], v[134:137], v[48:63]
	v_mfma_f32_32x32x16_bf16 v[32:47], v[186:189], v[134:137], v[32:47]
	v_mfma_f32_32x32x16_bf16 v[16:31], v[182:185], v[178:181], v[16:31]
	v_mfma_f32_32x32x16_bf16 v[0:15], v[186:189], v[178:181], v[0:15]
	ds_read_b128 v[134:137], v155 offset:49152
	ds_read_b128 v[178:181], v155 offset:53248
	ds_read_b128 v[182:185], v170
	ds_read_b128 v[186:189], v170 offset:4096
	v_mfma_f32_32x32x16_bf16 v[48:63], v[198:201], v[190:193], v[48:63]
	v_mfma_f32_32x32x16_bf16 v[32:47], v[202:205], v[190:193], v[32:47]
	v_mfma_f32_32x32x16_bf16 v[16:31], v[198:201], v[194:197], v[16:31]
	v_mfma_f32_32x32x16_bf16 v[0:15], v[202:205], v[194:197], v[0:15]
	ds_read_b128 v[190:193], v156 offset:49152
	ds_read_b128 v[194:197], v156 offset:53248
	ds_read_b128 v[198:201], v171
	ds_read_b128 v[202:205], v171 offset:4096
	s_waitcnt vmcnt(6)
	s_barrier
	s_waitcnt lgkmcnt(0)
	v_mfma_f32_32x32x16_bf16 v[48:63], v[182:185], v[134:137], v[48:63]
	v_mfma_f32_32x32x16_bf16 v[32:47], v[186:189], v[134:137], v[32:47]
	v_lshl_add_u64 v[134:135], v[150:151], 0, s[40:41]
	global_load_lds_dwordx4 v[134:135], off
	v_lshl_add_u64 v[134:135], v[150:151], 0, s[44:45]
	s_mov_b32 m0, s11
	s_nop 0
	global_load_lds_dwordx4 v[134:135], off
	v_mfma_f32_32x32x16_bf16 v[16:31], v[182:185], v[178:181], v[16:31]
	v_lshl_add_u64 v[134:135], v[150:151], 0, s[22:23]
	s_mov_b32 m0, s10
	s_nop 0
	global_load_lds_dwordx4 v[134:135], off
	v_lshl_add_u64 v[134:135], v[150:151], 0, s[56:57]
	s_mov_b32 m0, s9
	v_mfma_f32_32x32x16_bf16 v[0:15], v[186:189], v[178:181], v[0:15]
	global_load_lds_dwordx4 v[134:135], off
	v_lshl_add_u64 v[134:135], v[152:153], 0, s[40:41]
	s_mov_b32 m0, s8
	s_nop 0
	global_load_lds_dwordx4 v[134:135], off
	v_mfma_f32_32x32x16_bf16 v[48:63], v[198:201], v[190:193], v[48:63]
	v_lshl_add_u64 v[134:135], v[152:153], 0, s[44:45]
	s_mov_b32 m0, s7
	s_nop 0
	global_load_lds_dwordx4 v[134:135], off
	v_mfma_f32_32x32x16_bf16 v[32:47], v[202:205], v[190:193], v[32:47]
	v_mfma_f32_32x32x16_bf16 v[16:31], v[198:201], v[194:197], v[16:31]
	v_mfma_f32_32x32x16_bf16 v[0:15], v[202:205], v[194:197], v[0:15]
	ds_read_b128 v[134:137], v177
	ds_read_b128 v[150:153], v177 offset:4096
	ds_read_b128 v[178:181], v175
	ds_read_b128 v[182:185], v175 offset:4096
	ds_read_b128 v[186:189], v176
	ds_read_b128 v[190:193], v176 offset:4096
	ds_read_b128 v[194:197], v174
	ds_read_b128 v[172:175], v174 offset:4096
	s_waitcnt lgkmcnt(0)
	v_mfma_f32_32x32x16_bf16 v[48:63], v[178:181], v[134:137], v[48:63]
	v_mfma_f32_32x32x16_bf16 v[32:47], v[182:185], v[134:137], v[32:47]
	v_mfma_f32_32x32x16_bf16 v[16:31], v[178:181], v[150:153], v[16:31]
	v_mfma_f32_32x32x16_bf16 v[0:15], v[182:185], v[150:153], v[0:15]
	ds_read_b128 v[134:137], v130
	ds_read_b128 v[150:153], v130 offset:4096
	ds_read_b128 v[176:179], v131
	ds_read_b128 v[180:183], v131 offset:4096
	v_mfma_f32_32x32x16_bf16 v[48:63], v[194:197], v[186:189], v[48:63]
	v_mfma_f32_32x32x16_bf16 v[32:47], v[172:175], v[186:189], v[32:47]
	v_mfma_f32_32x32x16_bf16 v[16:31], v[194:197], v[190:193], v[16:31]
	v_mfma_f32_32x32x16_bf16 v[0:15], v[172:175], v[190:193], v[0:15]
	ds_read_b128 v[172:175], v132
	ds_read_b128 v[184:187], v132 offset:4096
	ds_read_b128 v[188:191], v133
	ds_read_b128 v[130:133], v133 offset:4096
	s_waitcnt vmcnt(6)
	s_barrier
;     DEVINL bf16_t* Z() const { return (bf16_t*)(ws + OFF_Z); }
; template <int NI>
; DEVINL void gemm_kloop(const bf16_t* __restrict__ A, int lda, const bf16_t* __restrict__ Bt, int ldb, int K, int m0, int n0,
;                        unsigned char* lds, f32x16 (&acc)[NI][2]) {
;     ...
;     if (nt >= 2) {
;         if (NI == 2) asm volatile("s_waitcnt vmcnt(6)" ::: "memory"); else asm volatile("s_waitcnt vmcnt(5)" ::: "memory");
;         __builtin_amdgcn_s_barrier();
;         compute(cur);
;         cur = (cur == 2) ? 0 : cur + 1;
;     }
;     asm volatile("s_waitcnt vmcnt(0)" ::: "memory");
;     __builtin_amdgcn_s_barrier();
;     compute(cur);
; template <int NI, int MODE>
; DEVINL void merge_tile(const Ctx& c, unsigned char* lds, int m0, int n0) {
;     ...
;             const bf16_t* gp = c.Z() + (size_t)(mbase + mi * 32 + r) * ZW + Z_GZ + br * DM + nbase;
; #pragma unroll
;             for (int ni = 0; ni < NI; ++ni)
; #pragma unroll
;                 for (int g = 0; g < 4; ++g) {
;                     const u32x2 gg = *(const u32x2*)(gp + ni * 32 + 8 * g + 4 * h);
	s_waitcnt lgkmcnt(0)
	v_mfma_f32_32x32x16_bf16 v[48:63], v[176:179], v[134:137], v[48:63]
	v_mfma_f32_32x32x16_bf16 v[32:47], v[180:183], v[134:137], v[32:47]
	v_mfma_f32_32x32x16_bf16 v[16:31], v[176:179], v[150:153], v[16:31]
	v_mfma_f32_32x32x16_bf16 v[0:15], v[180:183], v[150:153], v[0:15]
	v_mfma_f32_32x32x16_bf16 v[48:63], v[188:191], v[172:175], v[48:63]
	v_mfma_f32_32x32x16_bf16 v[32:47], v[130:133], v[172:175], v[32:47]
	v_mfma_f32_32x32x16_bf16 v[16:31], v[188:191], v[184:187], v[16:31]
	v_mfma_f32_32x32x16_bf16 v[0:15], v[130:133], v[184:187], v[0:15]
	ds_read_b128 v[130:133], v64
	ds_read_b128 v[134:137], v64 offset:4096
	ds_read_b128 v[150:153], v143 offset:32768
	ds_read_b128 v[172:175], v143 offset:36864
	ds_read_b128 v[176:179], v154
	ds_read_b128 v[180:183], v154 offset:4096
	ds_read_b128 v[184:187], v157 offset:32768
	ds_read_b128 v[188:191], v157 offset:36864
	s_waitcnt lgkmcnt(0)
	v_mfma_f32_32x32x16_bf16 v[48:63], v[150:153], v[130:133], v[48:63]
	v_mfma_f32_32x32x16_bf16 v[32:47], v[172:175], v[130:133], v[32:47]
	v_mfma_f32_32x32x16_bf16 v[16:31], v[150:153], v[134:137], v[16:31]
	v_mfma_f32_32x32x16_bf16 v[0:15], v[172:175], v[134:137], v[0:15]
	ds_read_b128 v[130:133], v155
	ds_read_b128 v[134:137], v155 offset:4096
	ds_read_b128 v[150:153], v158 offset:32768
	ds_read_b128 v[172:175], v158 offset:36864
	v_mfma_f32_32x32x16_bf16 v[48:63], v[184:187], v[176:179], v[48:63]
	v_mfma_f32_32x32x16_bf16 v[32:47], v[188:191], v[176:179], v[32:47]
	v_mfma_f32_32x32x16_bf16 v[16:31], v[184:187], v[180:183], v[16:31]
	v_mfma_f32_32x32x16_bf16 v[0:15], v[188:191], v[180:183], v[0:15]
	ds_read_b128 v[176:179], v156
	ds_read_b128 v[180:183], v156 offset:4096
	ds_read_b128 v[184:187], v159 offset:32768
	ds_read_b128 v[188:191], v159 offset:36864
	s_waitcnt vmcnt(0)
	s_barrier
	s_waitcnt lgkmcnt(0)
	v_mfma_f32_32x32x16_bf16 v[48:63], v[150:153], v[130:133], v[48:63]
	v_mfma_f32_32x32x16_bf16 v[32:47], v[172:175], v[130:133], v[32:47]
	v_mfma_f32_32x32x16_bf16 v[16:31], v[150:153], v[134:137], v[16:31]
	v_mfma_f32_32x32x16_bf16 v[0:15], v[172:175], v[134:137], v[0:15]
	v_mfma_f32_32x32x16_bf16 v[48:63], v[184:187], v[176:179], v[48:63]
	v_mfma_f32_32x32x16_bf16 v[32:47], v[188:191], v[176:179], v[32:47]
	v_mfma_f32_32x32x16_bf16 v[16:31], v[184:187], v[180:183], v[16:31]
	v_mfma_f32_32x32x16_bf16 v[0:15], v[188:191], v[180:183], v[0:15]
	ds_read_b128 v[130:133], v64 offset:49152
	ds_read_b128 v[134:137], v64 offset:53248
	ds_read_b128 v[150:153], v168
	ds_read_b128 v[172:175], v168 offset:4096
	ds_read_b128 v[176:179], v154 offset:49152
	ds_read_b128 v[180:183], v154 offset:53248
	ds_read_b128 v[184:187], v169
	ds_read_b128 v[188:191], v169 offset:4096
	s_waitcnt lgkmcnt(0)
	v_mfma_f32_32x32x16_bf16 v[48:63], v[150:153], v[130:133], v[48:63]
	v_mfma_f32_32x32x16_bf16 v[32:47], v[172:175], v[130:133], v[32:47]
	v_mfma_f32_32x32x16_bf16 v[48:63], v[184:187], v[176:179], v[48:63]
	v_mfma_f32_32x32x16_bf16 v[32:47], v[188:191], v[176:179], v[32:47]
	v_mfma_f32_32x32x16_bf16 v[16:31], v[150:153], v[134:137], v[16:31]
	v_mfma_f32_32x32x16_bf16 v[0:15], v[172:175], v[134:137], v[0:15]
	ds_read_b128 v[130:133], v155 offset:49152
	ds_read_b128 v[134:137], v155 offset:53248
	ds_read_b128 v[150:153], v170
	ds_read_b128 v[172:175], v170 offset:4096
	s_waitcnt lgkmcnt(0)
	v_mfma_f32_32x32x16_bf16 v[48:63], v[150:153], v[130:133], v[48:63]
	v_mfma_f32_32x32x16_bf16 v[32:47], v[172:175], v[130:133], v[32:47]
	v_lshl_add_u64 v[130:131], v[146:147], 0, s[66:67]
	v_mfma_f32_32x32x16_bf16 v[16:31], v[184:187], v[180:183], v[16:31]
	v_mfma_f32_32x32x16_bf16 v[0:15], v[188:191], v[180:183], v[0:15]
	ds_read_b128 v[176:179], v156 offset:49152
	ds_read_b128 v[154:157], v156 offset:53248
	ds_read_b128 v[180:183], v171
	ds_read_b128 v[168:171], v171 offset:4096
	v_mov_b64_e32 v[132:133], v[208:209]
	s_waitcnt lgkmcnt(0)
;     DEVINL bf16_t* Z() const { return (bf16_t*)(ws + OFF_Z); }
; DEVINL float bflo(unsigned u) { return __uint_as_float(u << 16); }
; DEVINL float bfhi(unsigned u) { return __uint_as_float(u & 0xffff0000u); }
; DEVINL float* mp_row(const Ctx& c, int t) { return (float*)(c.Z() + (size_t)t * ZW); }
; template <int NI, int MODE>
; DEVINL void merge_tile(const Ctx& c, unsigned char* lds, int m0, int n0) {
;     ...
;         for (int mi = 0; mi < 2; ++mi) {
;             const bf16_t* gp = c.Z() + (size_t)(mbase + mi * 32 + r) * ZW + Z_GZ + br * DM + nbase;
; #pragma unroll
;             for (int ni = 0; ni < NI; ++ni)
; #pragma unroll
;                 for (int g = 0; g < 4; ++g) {
;                     const u32x2 gg = *(const u32x2*)(gp + ni * 32 + 8 * g + 4 * h);
;                     mer[ni][mi][4 * g + 0] += bflo(gg[0]) * acc[ni][mi][4 * g + 0];
;                     mer[ni][mi][4 * g + 1] += bfhi(gg[0]) * acc[ni][mi][4 * g + 1];
;                     mer[ni][mi][4 * g + 2] += bflo(gg[1]) * acc[ni][mi][4 * g + 2];
;                     mer[ni][mi][4 * g + 3] += bfhi(gg[1]) * acc[ni][mi][4 * g + 3];
;                 }
;         }
;     }
;     if (MODE == 0) {
; #pragma unroll
;         for (int mi = 0; mi < 2; ++mi) {
;             float* pp = mp_row(c, mbase + mi * 32 + r) + nbase;
; #pragma unroll
;             for (int ni = 0; ni < NI; ++ni)
; #pragma unroll
;                 for (int g = 0; g < 4; ++g) {
;                     f32x4 v = {mer[ni][mi][4 * g], mer[ni][mi][4 * g + 1], mer[ni][mi][4 * g + 2], mer[ni][mi][4 * g + 3]};
;                     *(f32x4*)(pp + ni * 32 + 8 * g + 4 * h) = v;
;                 }
;         }
	v_mfma_f32_32x32x16_bf16 v[48:63], v[180:183], v[176:179], v[48:63]
	v_mfma_f32_32x32x16_bf16 v[16:31], v[150:153], v[134:137], v[16:31]
	v_mfma_f32_32x32x16_bf16 v[0:15], v[172:175], v[134:137], v[0:15]
	s_nop 0
	v_lshlrev_b32_e32 v134, 16, v132
	v_and_b32_e32 v135, 0xffff0000, v132
	s_nop 6
	v_fma_f32 v126, v48, v134, v126
	v_fma_f32 v127, v49, v135, v127
	v_lshlrev_b32_e32 v48, 16, v133
	v_and_b32_e32 v49, 0xffff0000, v133
	v_pk_fma_f32 v[128:129], v[50:51], v[48:49], v[128:129]
	v_mov_b64_e32 v[48:49], v[210:211]
	v_mfma_f32_32x32x16_bf16 v[32:47], v[168:171], v[176:179], v[32:47]
	s_nop 0
	v_lshlrev_b32_e32 v50, 16, v48
	v_and_b32_e32 v51, 0xffff0000, v48
	v_lshlrev_b32_e32 v48, 16, v49
	v_and_b32_e32 v49, 0xffff0000, v49
	v_pk_fma_f32 v[124:125], v[54:55], v[48:49], v[124:125]
	v_mov_b64_e32 v[48:49], v[212:213]
	v_pk_fma_f32 v[122:123], v[52:53], v[50:51], v[122:123]
	v_mfma_f32_32x32x16_bf16 v[16:31], v[180:183], v[154:157], v[16:31]
	s_nop 0
	v_lshlrev_b32_e32 v50, 16, v48
	v_and_b32_e32 v51, 0xffff0000, v48
	v_lshlrev_b32_e32 v48, 16, v49
	v_and_b32_e32 v49, 0xffff0000, v49
	v_pk_fma_f32 v[120:121], v[58:59], v[48:49], v[120:121]
	v_mov_b64_e32 v[48:49], v[214:215]
	v_pk_fma_f32 v[118:119], v[56:57], v[50:51], v[118:119]
	v_mfma_f32_32x32x16_bf16 v[0:15], v[168:171], v[154:157], v[0:15]
	s_nop 0
	v_lshlrev_b32_e32 v50, 16, v48
	v_and_b32_e32 v51, 0xffff0000, v48
	v_lshlrev_b32_e32 v48, 16, v49
	v_and_b32_e32 v49, 0xffff0000, v49
	v_pk_fma_f32 v[116:117], v[62:63], v[48:49], v[116:117]
	v_mov_b64_e32 v[48:49], v[216:217]
	v_pk_fma_f32 v[114:115], v[60:61], v[50:51], v[114:115]
	s_nop 0
	v_lshlrev_b32_e32 v50, 16, v48
	v_and_b32_e32 v51, 0xffff0000, v48
	v_pk_fma_f32 v[110:111], v[32:33], v[50:51], v[110:111]
	v_lshlrev_b32_e32 v32, 16, v49
	v_and_b32_e32 v33, 0xffff0000, v49
	v_pk_fma_f32 v[112:113], v[34:35], v[32:33], v[112:113]
	v_mov_b64_e32 v[32:33], v[218:219]
	s_nop 0
	v_lshlrev_b32_e32 v34, 16, v32
	v_and_b32_e32 v35, 0xffff0000, v32
	v_lshlrev_b32_e32 v32, 16, v33
	v_and_b32_e32 v33, 0xffff0000, v33
	v_pk_fma_f32 v[108:109], v[38:39], v[32:33], v[108:109]
	v_mov_b64_e32 v[32:33], v[228:229]
	v_pk_fma_f32 v[106:107], v[36:37], v[34:35], v[106:107]
	s_nop 0
	v_lshlrev_b32_e32 v34, 16, v32
	v_and_b32_e32 v35, 0xffff0000, v32
	v_lshlrev_b32_e32 v32, 16, v33
	v_and_b32_e32 v33, 0xffff0000, v33
	v_pk_fma_f32 v[104:105], v[42:43], v[32:33], v[104:105]
	v_mov_b64_e32 v[32:33], v[254:255]
	v_pk_fma_f32 v[102:103], v[40:41], v[34:35], v[102:103]
	s_nop 0
	v_lshlrev_b32_e32 v34, 16, v32
	v_and_b32_e32 v35, 0xffff0000, v32
	v_lshlrev_b32_e32 v32, 16, v33
	v_and_b32_e32 v33, 0xffff0000, v33
	v_pk_fma_f32 v[88:89], v[46:47], v[32:33], v[88:89]
	v_lshl_add_u64 v[32:33], v[148:149], 0, s[66:67]
	v_pk_fma_f32 v[86:87], v[44:45], v[34:35], v[86:87]
	v_mov_b64_e32 v[34:35], v[230:231]
	s_nop 0
	v_lshlrev_b32_e32 v36, 16, v34
	v_and_b32_e32 v37, 0xffff0000, v34
	v_pk_fma_f32 v[98:99], v[16:17], v[36:37], v[98:99]
	v_lshlrev_b32_e32 v16, 16, v35
	v_and_b32_e32 v17, 0xffff0000, v35
	v_pk_fma_f32 v[100:101], v[18:19], v[16:17], v[100:101]
	v_mov_b64_e32 v[16:17], v[232:233]
	s_nop 0
	v_lshlrev_b32_e32 v18, 16, v16
	v_and_b32_e32 v19, 0xffff0000, v16
	v_lshlrev_b32_e32 v16, 16, v17
	v_and_b32_e32 v17, 0xffff0000, v17
	v_pk_fma_f32 v[96:97], v[22:23], v[16:17], v[96:97]
	v_mov_b64_e32 v[16:17], v[234:235]
	v_pk_fma_f32 v[94:95], v[20:21], v[18:19], v[94:95]
	s_nop 0
	v_lshlrev_b32_e32 v18, 16, v16
	v_and_b32_e32 v19, 0xffff0000, v16
	v_lshlrev_b32_e32 v16, 16, v17
	v_and_b32_e32 v17, 0xffff0000, v17
	v_pk_fma_f32 v[92:93], v[26:27], v[16:17], v[92:93]
	v_mov_b64_e32 v[16:17], v[236:237]
	v_pk_fma_f32 v[90:91], v[24:25], v[18:19], v[90:91]
	s_nop 0
	v_lshlrev_b32_e32 v18, 16, v16
	v_and_b32_e32 v19, 0xffff0000, v16
	v_lshlrev_b32_e32 v16, 16, v17
	v_and_b32_e32 v17, 0xffff0000, v17
	v_pk_fma_f32 v[84:85], v[30:31], v[16:17], v[84:85]
	v_mov_b64_e32 v[16:17], v[248:249]
	v_pk_fma_f32 v[82:83], v[28:29], v[18:19], v[82:83]
	s_nop 0
	v_lshlrev_b32_e32 v18, 16, v16
	v_and_b32_e32 v19, 0xffff0000, v16
	v_pk_fma_f32 v[78:79], v[0:1], v[18:19], v[78:79]
	v_lshlrev_b32_e32 v0, 16, v17
	v_and_b32_e32 v1, 0xffff0000, v17
	v_pk_fma_f32 v[80:81], v[2:3], v[0:1], v[80:81]
	v_mov_b64_e32 v[0:1], v[250:251]
	s_nop 0
	v_lshlrev_b32_e32 v2, 16, v0
	v_and_b32_e32 v3, 0xffff0000, v0
	v_lshlrev_b32_e32 v0, 16, v1
	v_and_b32_e32 v1, 0xffff0000, v1
	v_pk_fma_f32 v[76:77], v[6:7], v[0:1], v[76:77]
	v_mov_b64_e32 v[0:1], v[252:253]
	v_pk_fma_f32 v[74:75], v[4:5], v[2:3], v[74:75]
	s_nop 0
	v_lshlrev_b32_e32 v2, 16, v0
	v_and_b32_e32 v3, 0xffff0000, v0
	v_lshlrev_b32_e32 v0, 16, v1
	v_and_b32_e32 v1, 0xffff0000, v1
	v_pk_fma_f32 v[72:73], v[10:11], v[0:1], v[72:73]
	v_mov_b64_e32 v[0:1], v[242:243]
	v_pk_fma_f32 v[70:71], v[8:9], v[2:3], v[70:71]
	s_nop 0
	v_lshlrev_b32_e32 v2, 16, v0
	v_and_b32_e32 v3, 0xffff0000, v0
	v_lshlrev_b32_e32 v0, 16, v1
	v_and_b32_e32 v1, 0xffff0000, v1
	v_pk_fma_f32 v[66:67], v[12:13], v[2:3], v[66:67]
	v_pk_fma_f32 v[68:69], v[14:15], v[0:1], v[68:69]
	s_cbranch_scc1 .LBB0_284
	v_readlane_b32 s6, v247, 7
	v_readlane_b32 s7, v247, 8
	v_lshlrev_b64 v[2:3], 2, v[140:141]
	v_lshlrev_b32_e32 v64, 2, v142
	v_lshl_add_u64 v[0:1], s[6:7], 0, v[144:145]
	v_lshl_add_u64 v[0:1], v[0:1], 0, v[2:3]
	v_lshl_add_u64 v[0:1], v[0:1], 0, v[64:65]
	global_store_dwordx4 v[0:1], v[126:129], off
	global_store_dwordx4 v[0:1], v[122:125], off offset:32
	global_store_dwordx4 v[0:1], v[118:121], off offset:64
	global_store_dwordx4 v[0:1], v[114:117], off offset:96
	global_store_dwordx4 v[0:1], v[110:113], off offset:128
	global_store_dwordx4 v[0:1], v[106:109], off offset:160
	global_store_dwordx4 v[0:1], v[102:105], off offset:192
	global_store_dwordx4 v[0:1], v[86:89], off offset:224
	v_lshl_add_u64 v[0:1], s[6:7], 0, v[138:139]
	v_lshl_add_u64 v[0:1], v[0:1], 0, v[2:3]
	s_add_i32 s0, s0, s28
	v_lshl_add_u64 v[0:1], v[0:1], 0, v[64:65]
	s_cmpk_gt_i32 s0, 0x21f
	s_movk_i32 s49, 0x4400
	global_store_dwordx4 v[0:1], v[98:101], off
	global_store_dwordx4 v[0:1], v[94:97], off offset:32
	global_store_dwordx4 v[0:1], v[90:93], off offset:64
	global_store_dwordx4 v[0:1], v[82:85], off offset:96
	global_store_dwordx4 v[0:1], v[78:81], off offset:128
	global_store_dwordx4 v[0:1], v[74:77], off offset:160
	global_store_dwordx4 v[0:1], v[70:73], off offset:192
	global_store_dwordx4 v[0:1], v[66:69], off offset:224
	s_cbranch_scc0 .LBB0_283
